# DIFF attn: predictive re-reference (dl=max(0,pmax,min(pmax+40,120))) to halve rescale events on steep ALiBi heads
# speedup vs baseline: 1.0025x; 1.0025x over previous
.LBB0_1430:
	v_max_f32_e32 v2, v129, v129
	v_max_f32_e32 v129, v128, v128
	v_max_f32_e32 v2, v129, v2
	v_max3_f32 v2, v2, v130, v131
	v_max3_f32 v2, v2, v132, v133
	v_max3_f32 v2, v2, v134, v135
	v_max3_f32 v2, v2, v136, v137
	v_max3_f32 v2, v2, v138, v139
	v_max3_f32 v2, v2, v140, v141
	v_max3_f32 v2, v2, v142, v197
	v_max3_f32 v2, v2, v112, v113
	v_max3_f32 v2, v2, v114, v115
	v_max3_f32 v2, v2, v116, v117
	v_max3_f32 v2, v2, v118, v119
	v_max3_f32 v2, v2, v120, v121
	v_max3_f32 v2, v2, v122, v123
	v_max3_f32 v2, v2, v124, v125
	v_max3_f32 v2, v2, v126, v127
	v_mov_b32_e32 v113, v2
	s_nop 1
	v_permlane32_swap_b32_e32 v2, v113
	v_max_f32_e32 v113, v113, v113
	v_max_f32_e32 v2, v2, v2
	v_max_f32_e32 v2, v2, v113
	v_cmp_ge_f32_e32 vcc, s68, v2
	s_cmp_eq_u64 vcc, exec
	v_mov_b32_e32 v225, 1.0
	s_cbranch_scc1 .LBB0_1432
	v_max_f32_e32 v2, v2, v2
	v_add_f32_e32 v245, 0x42200000, v2
	v_min_f32_e32 v245, 0x42f00000, v245
	v_max3_f32 v2, v245, v2, 0
	v_mov_b32_e32 v112, v80
	v_exp_f32_e64 v225, -v2
	v_mov_b32_e32 v80, v81
	v_mov_b32_e32 v81, v82
	v_mov_b32_e32 v82, v83
	v_mov_b32_e32 v83, v84
	v_mov_b32_e32 v84, v85
	v_mov_b32_e32 v85, v86
	v_mov_b32_e32 v86, v87
	v_mov_b32_e32 v87, v88
	v_mov_b32_e32 v88, v89
	v_mov_b32_e32 v89, v90
	v_mov_b32_e32 v90, v91
	v_mov_b32_e32 v91, v92
	v_mov_b32_e32 v113, v96
	v_mov_b32_e32 v96, v97
	v_mov_b32_e32 v97, v98
	v_pk_add_f32 v[116:117], v[80:81], v[2:3] op_sel_hi:[1,0] neg_lo:[0,1] neg_hi:[0,1]
	v_mov_b32_e32 v80, v99
	v_mov_b32_e32 v81, v100
	v_pk_add_f32 v[118:119], v[82:83], v[2:3] op_sel_hi:[1,0] neg_lo:[0,1] neg_hi:[0,1]
	v_mov_b32_e32 v82, v101
	v_mov_b32_e32 v83, v102
	v_pk_add_f32 v[120:121], v[84:85], v[2:3] op_sel_hi:[1,0] neg_lo:[0,1] neg_hi:[0,1]
	v_mov_b32_e32 v84, v103
	v_mov_b32_e32 v85, v104
	v_pk_add_f32 v[122:123], v[86:87], v[2:3] op_sel_hi:[1,0] neg_lo:[0,1] neg_hi:[0,1]
	v_mov_b32_e32 v86, v105
	v_mov_b32_e32 v87, v106
	v_pk_add_f32 v[124:125], v[88:89], v[2:3] op_sel_hi:[1,0] neg_lo:[0,1] neg_hi:[0,1]
	v_mov_b32_e32 v88, v107
	v_mov_b32_e32 v89, v108
	v_pk_add_f32 v[128:129], v[90:91], v[2:3] op_sel_hi:[1,0] neg_lo:[0,1] neg_hi:[0,1]
	v_mov_b32_e32 v90, v109
	v_mov_b32_e32 v91, v110
	v_mov_b32_e32 v92, v93
	v_mov_b32_e32 v93, v94
	v_pk_add_f32 v[112:113], v[112:113], v[2:3] op_sel_hi:[1,0] neg_lo:[0,1] neg_hi:[0,1]
	v_pk_add_f32 v[114:115], v[96:97], v[2:3] op_sel_hi:[1,0] neg_lo:[0,1] neg_hi:[0,1]
	v_pk_add_f32 v[80:81], v[80:81], v[2:3] op_sel_hi:[1,0] neg_lo:[0,1] neg_hi:[0,1]
	v_pk_add_f32 v[82:83], v[82:83], v[2:3] op_sel_hi:[1,0] neg_lo:[0,1] neg_hi:[0,1]
	v_pk_add_f32 v[84:85], v[84:85], v[2:3] op_sel_hi:[1,0] neg_lo:[0,1] neg_hi:[0,1]
	v_pk_add_f32 v[86:87], v[86:87], v[2:3] op_sel_hi:[1,0] neg_lo:[0,1] neg_hi:[0,1]
	v_pk_add_f32 v[88:89], v[88:89], v[2:3] op_sel_hi:[1,0] neg_lo:[0,1] neg_hi:[0,1]
	v_pk_add_f32 v[90:91], v[90:91], v[2:3] op_sel_hi:[1,0] neg_lo:[0,1] neg_hi:[0,1]
	v_pk_add_f32 v[130:131], v[92:93], v[2:3] op_sel_hi:[1,0] neg_lo:[0,1] neg_hi:[0,1]
	v_add_f32_e32 v221, v221, v2
	v_sub_f32_e32 v111, v197, v2
	v_sub_f32_e32 v95, v127, v2
	v_mov_b32_e32 v97, v114
	v_mov_b32_e32 v98, v115
	v_mov_b32_e32 v99, v80
	v_mov_b32_e32 v100, v81
	v_mov_b32_e32 v101, v82
	v_mov_b32_e32 v102, v83
	v_mov_b32_e32 v103, v84
	v_mov_b32_e32 v104, v85
	v_mov_b32_e32 v105, v86
	v_mov_b32_e32 v106, v87
	v_mov_b32_e32 v107, v88
	v_mov_b32_e32 v108, v89
	v_mov_b32_e32 v109, v90
	v_mov_b32_e32 v110, v91
	v_mov_b32_e32 v81, v116
	v_mov_b32_e32 v82, v117
	v_mov_b32_e32 v83, v118
	v_mov_b32_e32 v84, v119
	v_mov_b32_e32 v85, v120
	v_mov_b32_e32 v86, v121
	v_mov_b32_e32 v87, v122
	v_mov_b32_e32 v88, v123
	v_mov_b32_e32 v89, v124
	v_mov_b32_e32 v90, v125
	v_mov_b32_e32 v91, v128
	v_mov_b32_e32 v92, v129
	v_mov_b32_e32 v93, v130
	v_mov_b32_e32 v94, v131
	v_mov_b32_e32 v128, v113
	s_branch .LBB0_1433

.LBB0_1445:
	v_max_f32_e32 v129, v129, v129
	v_max_f32_e32 v143, v128, v128
	v_max_f32_e32 v129, v143, v129
	v_max3_f32 v129, v129, v130, v131
	v_max3_f32 v129, v129, v132, v133
	v_max3_f32 v129, v129, v134, v135
	v_max3_f32 v129, v129, v136, v137
	v_max3_f32 v129, v129, v138, v139
	v_max3_f32 v129, v129, v140, v141
	v_max3_f32 v129, v129, v142, v197
	v_max3_f32 v113, v129, v112, v113
	v_max3_f32 v113, v113, v114, v115
	v_max3_f32 v113, v113, v116, v117
	v_max3_f32 v113, v113, v118, v119
	v_max3_f32 v113, v113, v120, v121
	v_max3_f32 v113, v113, v122, v123
	v_max3_f32 v113, v113, v124, v125
	v_max3_f32 v113, v113, v126, v127
	v_mov_b32_e32 v114, v113
	s_nop 1
	v_permlane32_swap_b32_e32 v113, v114
	v_max_f32_e32 v114, v114, v114
	v_max_f32_e32 v113, v113, v113
	v_max_f32_e32 v113, v113, v114
	v_cmp_ge_f32_e32 vcc, s68, v113
	s_cmp_eq_u64 vcc, exec
	v_mov_b32_e32 v196, 1.0
	s_cbranch_scc1 .LBB0_1447
	v_mov_b32_e32 v114, v80
	v_max_f32_e32 v80, v113, v113
	v_mov_b32_e32 v115, v96
	v_add_f32_e32 v245, 0x42200000, v80
	v_min_f32_e32 v245, 0x42f00000, v245
	v_max3_f32 v80, v245, v80, 0
	v_mov_b32_e32 v96, v97
	v_mov_b32_e32 v97, v98
	v_exp_f32_e64 v196, -v80
	v_pk_add_f32 v[112:113], v[114:115], v[80:81] op_sel_hi:[1,0] neg_lo:[0,1] neg_hi:[0,1]
	v_pk_add_f32 v[114:115], v[96:97], v[80:81] op_sel_hi:[1,0] neg_lo:[0,1] neg_hi:[0,1]
	v_mov_b32_e32 v96, v81
	v_mov_b32_e32 v97, v82
	v_mov_b32_e32 v82, v83
	v_mov_b32_e32 v83, v84
	v_mov_b32_e32 v84, v85
	v_mov_b32_e32 v85, v86
	v_mov_b32_e32 v86, v87
	v_mov_b32_e32 v87, v88
	v_mov_b32_e32 v88, v89
	v_mov_b32_e32 v89, v90
	v_mov_b32_e32 v90, v91
	v_mov_b32_e32 v91, v92
	v_pk_add_f32 v[116:117], v[96:97], v[80:81] op_sel_hi:[1,0] neg_lo:[0,1] neg_hi:[0,1]
	v_mov_b32_e32 v96, v99
	v_mov_b32_e32 v97, v100
	v_pk_add_f32 v[120:121], v[82:83], v[80:81] op_sel_hi:[1,0] neg_lo:[0,1] neg_hi:[0,1]
	v_mov_b32_e32 v82, v101
	v_mov_b32_e32 v83, v102
	v_pk_add_f32 v[122:123], v[84:85], v[80:81] op_sel_hi:[1,0] neg_lo:[0,1] neg_hi:[0,1]
	v_mov_b32_e32 v84, v103
	v_mov_b32_e32 v85, v104
	v_pk_add_f32 v[124:125], v[86:87], v[80:81] op_sel_hi:[1,0] neg_lo:[0,1] neg_hi:[0,1]
	v_mov_b32_e32 v86, v105
	v_mov_b32_e32 v87, v106
	v_pk_add_f32 v[128:129], v[88:89], v[80:81] op_sel_hi:[1,0] neg_lo:[0,1] neg_hi:[0,1]
	v_mov_b32_e32 v88, v107
	v_mov_b32_e32 v89, v108
	v_pk_add_f32 v[130:131], v[90:91], v[80:81] op_sel_hi:[1,0] neg_lo:[0,1] neg_hi:[0,1]
	v_mov_b32_e32 v90, v109
	v_mov_b32_e32 v91, v110
	v_mov_b32_e32 v92, v93
	v_mov_b32_e32 v93, v94
	v_pk_add_f32 v[118:119], v[96:97], v[80:81] op_sel_hi:[1,0] neg_lo:[0,1] neg_hi:[0,1]
	v_pk_add_f32 v[82:83], v[82:83], v[80:81] op_sel_hi:[1,0] neg_lo:[0,1] neg_hi:[0,1]
	v_pk_add_f32 v[84:85], v[84:85], v[80:81] op_sel_hi:[1,0] neg_lo:[0,1] neg_hi:[0,1]
	v_pk_add_f32 v[86:87], v[86:87], v[80:81] op_sel_hi:[1,0] neg_lo:[0,1] neg_hi:[0,1]
	v_pk_add_f32 v[88:89], v[88:89], v[80:81] op_sel_hi:[1,0] neg_lo:[0,1] neg_hi:[0,1]
	v_pk_add_f32 v[90:91], v[90:91], v[80:81] op_sel_hi:[1,0] neg_lo:[0,1] neg_hi:[0,1]
	v_pk_add_f32 v[132:133], v[92:93], v[80:81] op_sel_hi:[1,0] neg_lo:[0,1] neg_hi:[0,1]
	v_add_f32_e32 v221, v221, v80
	v_sub_f32_e32 v111, v197, v80
	v_sub_f32_e32 v95, v127, v80
	v_mov_b32_e32 v97, v114
	v_mov_b32_e32 v98, v115
	v_mov_b32_e32 v99, v118
	v_mov_b32_e32 v100, v119
	v_mov_b32_e32 v101, v82
	v_mov_b32_e32 v102, v83
	v_mov_b32_e32 v103, v84
	v_mov_b32_e32 v104, v85
	v_mov_b32_e32 v105, v86
	v_mov_b32_e32 v106, v87
	v_mov_b32_e32 v107, v88
	v_mov_b32_e32 v108, v89
	v_mov_b32_e32 v109, v90
	v_mov_b32_e32 v110, v91
	v_mov_b32_e32 v81, v116
	v_mov_b32_e32 v82, v117
	v_mov_b32_e32 v83, v120
	v_mov_b32_e32 v84, v121
	v_mov_b32_e32 v85, v122
	v_mov_b32_e32 v86, v123
	v_mov_b32_e32 v87, v124
	v_mov_b32_e32 v88, v125
	v_mov_b32_e32 v89, v128
	v_mov_b32_e32 v90, v129
	v_mov_b32_e32 v91, v130
	v_mov_b32_e32 v92, v131
	v_mov_b32_e32 v93, v132
	v_mov_b32_e32 v94, v133
	v_mov_b32_e32 v128, v113
	s_branch .LBB0_1448

	.amdhsa_kernel _Z8mega_fwd4Args
		.amdhsa_group_segment_fixed_size 0
		.amdhsa_private_segment_fixed_size 0
		.amdhsa_kernarg_size 440
		.amdhsa_user_sgpr_count 2
		.amdhsa_user_sgpr_dispatch_ptr 0
		.amdhsa_user_sgpr_queue_ptr 0
		.amdhsa_user_sgpr_kernarg_segment_ptr 1
		.amdhsa_user_sgpr_dispatch_id 0
		.amdhsa_user_sgpr_kernarg_preload_length 0
		.amdhsa_user_sgpr_kernarg_preload_offset 0
		.amdhsa_user_sgpr_private_segment_size 0
		.amdhsa_uses_dynamic_stack 0
		.amdhsa_enable_private_segment 0
		.amdhsa_system_sgpr_workgroup_id_x 1
		.amdhsa_system_sgpr_workgroup_id_y 0
		.amdhsa_system_sgpr_workgroup_id_z 0
		.amdhsa_system_sgpr_workgroup_info 0
		.amdhsa_system_vgpr_workitem_id 2
		.amdhsa_next_free_vgpr 248
		.amdhsa_next_free_sgpr 98
		.amdhsa_accum_offset 248
		.amdhsa_reserve_vcc 1
		.amdhsa_float_round_mode_32 0
		.amdhsa_float_round_mode_16_64 0
		.amdhsa_float_denorm_mode_32 3
		.amdhsa_float_denorm_mode_16_64 3
		.amdhsa_dx10_clamp 1
		.amdhsa_ieee_mode 1
		.amdhsa_fp16_overflow 0
		.amdhsa_tg_split 0
		.amdhsa_exception_fp_ieee_invalid_op 0
		.amdhsa_exception_fp_denorm_src 0
		.amdhsa_exception_fp_ieee_div_zero 0
		.amdhsa_exception_fp_ieee_overflow 0
		.amdhsa_exception_fp_ieee_underflow 0
		.amdhsa_exception_fp_ieee_inexact 0
		.amdhsa_exception_int_div_zero 0
	.end_amdhsa_kernel

amdhsa.kernels:
  - .agpr_count:     0
    .args:
      - .offset:         0
        .size:           184
        .value_kind:     by_value
      - .offset:         184
        .size:           4
        .value_kind:     hidden_block_count_x
      - .offset:         188
        .size:           4
        .value_kind:     hidden_block_count_y
      - .offset:         192
        .size:           4
        .value_kind:     hidden_block_count_z
      - .offset:         196
        .size:           2
        .value_kind:     hidden_group_size_x
      - .offset:         198
        .size:           2
        .value_kind:     hidden_group_size_y
      - .offset:         200
        .size:           2
        .value_kind:     hidden_group_size_z
      - .offset:         202
        .size:           2
        .value_kind:     hidden_remainder_x
      - .offset:         204
        .size:           2
        .value_kind:     hidden_remainder_y
      - .offset:         206
        .size:           2
        .value_kind:     hidden_remainder_z
      - .offset:         224
        .size:           8
        .value_kind:     hidden_global_offset_x
      - .offset:         232
        .size:           8
        .value_kind:     hidden_global_offset_y
      - .offset:         240
        .size:           8
        .value_kind:     hidden_global_offset_z
      - .offset:         248
        .size:           2
        .value_kind:     hidden_grid_dims
      - .offset:         272
        .size:           8
        .value_kind:     hidden_multigrid_sync_arg
      - .offset:         304
        .size:           4
        .value_kind:     hidden_dynamic_lds_size
    .group_segment_fixed_size: 0
    .kernarg_segment_align: 8
    .kernarg_segment_size: 440
    .language:       OpenCL C
    .language_version:
      - 2
      - 0
    .max_flat_workgroup_size: 512
    .name:           _Z8mega_fwd4Args
    .private_segment_fixed_size: 0
    .sgpr_count:     104
    .sgpr_spill_count: 37
    .symbol:         _Z8mega_fwd4Args.kd
    .uniform_work_group_size: 1
    .uses_dynamic_stack: false
    .vgpr_count:     248
    .vgpr_spill_count: 0
    .wavefront_size: 64
